# P3/P5 EpiRes epilogues: all 16 residual loads issued up front, counted waits, permlane swaps instead of ds_bpermute
# speedup vs baseline: 1.0043x; 1.0043x over previous
.LBB0_688:
	v_lshl_add_u32 v146, s38, 8, v148
	v_mov_b32_e32 v147, 0
	v_lshl_add_u32 v144, s6, 8, v150
	v_mov_b32_e32 v145, 0
	v_lshlrev_b64 v[156:157], 11, v[146:147]
	v_lshl_add_u64 v[156:157], s[10:11], 0, v[156:157]
	v_lshl_add_u64 v[246:247], v[144:145], 1, v[156:157]
	v_mov_b32_e32 v248, v246
	v_mov_b32_e32 v249, v247
	v_lshlrev_b64 v[156:157], 6, v[146:147]
	v_lshl_add_u64 v[242:243], s[12:13], 0, v[156:157]
	s_lshl_b32 s38, s6, 2
	s_add_i32 s38, s38, s36
	s_lshl_b32 s38, s38, 2
	s_mov_b32 s39, 0
	v_lshl_add_u64 v[242:243], v[242:243], 0, s[38:39]
	s_mov_b64 s[6:7], 0x2000
	v_lshl_add_u64 v[244:245], v[242:243], 0, s[6:7]
	s_mov_b64 s[38:39], 0x8000
	s_mov_b64 s[6:7], 0x28000
	global_load_dwordx4 v[160:163], v[246:247], off
	global_load_dwordx4 v[164:167], v[246:247], off offset:256
	v_lshl_add_u64 v[246:247], v[246:247], 0, s[38:39]
	global_load_dwordx4 v[168:171], v[246:247], off
	global_load_dwordx4 v[172:175], v[246:247], off offset:256
	v_lshl_add_u64 v[246:247], v[246:247], 0, s[38:39]
	global_load_dwordx4 v[176:179], v[246:247], off
	global_load_dwordx4 v[180:183], v[246:247], off offset:256
	v_lshl_add_u64 v[246:247], v[246:247], 0, s[38:39]
	global_load_dwordx4 v[184:187], v[246:247], off
	global_load_dwordx4 v[188:191], v[246:247], off offset:256
	v_lshl_add_u64 v[246:247], v[246:247], 0, s[6:7]
	global_load_dwordx4 v[192:195], v[246:247], off
	global_load_dwordx4 v[196:199], v[246:247], off offset:256
	v_lshl_add_u64 v[246:247], v[246:247], 0, s[38:39]
	global_load_dwordx4 v[200:203], v[246:247], off
	global_load_dwordx4 v[204:207], v[246:247], off offset:256
	v_lshl_add_u64 v[246:247], v[246:247], 0, s[38:39]
	global_load_dwordx4 v[208:211], v[246:247], off
	global_load_dwordx4 v[212:215], v[246:247], off offset:256
	v_lshl_add_u64 v[246:247], v[246:247], 0, s[38:39]
	global_load_dwordx4 v[216:219], v[246:247], off
	global_load_dwordx4 v[220:223], v[246:247], off offset:256
	s_waitcnt vmcnt(14)
	v_lshlrev_b32_e32 v226, 16, v160
	v_and_b32_e32 v227, 0xffff0000, v160
	v_lshlrev_b32_e32 v228, 16, v161
	v_and_b32_e32 v229, 0xffff0000, v161
	v_lshlrev_b32_e32 v230, 16, v162
	v_and_b32_e32 v231, 0xffff0000, v162
	v_lshlrev_b32_e32 v232, 16, v163
	v_and_b32_e32 v233, 0xffff0000, v163
	v_lshlrev_b32_e32 v234, 16, v164
	v_and_b32_e32 v235, 0xffff0000, v164
	v_lshlrev_b32_e32 v236, 16, v165
	v_and_b32_e32 v237, 0xffff0000, v165
	v_lshlrev_b32_e32 v238, 16, v166
	v_and_b32_e32 v239, 0xffff0000, v166
	v_lshlrev_b32_e32 v240, 16, v167
	v_and_b32_e32 v241, 0xffff0000, v167
	v_pk_add_f32 v[124:125], v[124:125], v[226:227]
	v_pk_add_f32 v[126:127], v[126:127], v[228:229]
	v_pk_add_f32 v[120:121], v[120:121], v[230:231]
	v_pk_add_f32 v[122:123], v[122:123], v[232:233]
	v_pk_add_f32 v[116:117], v[116:117], v[234:235]
	v_pk_add_f32 v[118:119], v[118:119], v[236:237]
	v_pk_add_f32 v[112:113], v[112:113], v[238:239]
	v_pk_add_f32 v[114:115], v[114:115], v[240:241]
	v_mul_f32_e32 v226, v125, v125
	v_mul_f32_e32 v227, v127, v127
	v_mul_f32_e32 v228, v121, v121
	v_mul_f32_e32 v229, v123, v123
	v_mul_f32_e32 v234, v117, v117
	v_mul_f32_e32 v235, v119, v119
	v_mul_f32_e32 v236, v113, v113
	v_mul_f32_e32 v237, v115, v115
	v_fmac_f32_e32 v226, v124, v124
	v_fmac_f32_e32 v227, v126, v126
	v_fmac_f32_e32 v228, v120, v120
	v_fmac_f32_e32 v229, v122, v122
	v_fmac_f32_e32 v234, v116, v116
	v_fmac_f32_e32 v235, v118, v118
	v_fmac_f32_e32 v236, v112, v112
	v_fmac_f32_e32 v237, v114, v114
	v_add_f32_e32 v226, v226, v227
	v_add_f32_e32 v234, v234, v235
	v_add_f32_e32 v226, v228, v226
	v_add_f32_e32 v234, v236, v234
	v_add_f32_e32 v226, v229, v226
	v_add_f32_e32 v234, v237, v234
	v_add_f32_e32 v250, v226, v234
	v_cvt_pk_bf16_f32 v230, v124, v125
	v_cvt_pk_bf16_f32 v231, v126, v127
	v_cvt_pk_bf16_f32 v232, v120, v121
	v_cvt_pk_bf16_f32 v233, v122, v123
	v_cvt_pk_bf16_f32 v238, v116, v117
	v_cvt_pk_bf16_f32 v239, v118, v119
	v_cvt_pk_bf16_f32 v240, v112, v113
	v_cvt_pk_bf16_f32 v241, v114, v115
	v_mov_b32_e32 v251, v250
	global_store_dwordx4 v[248:249], v[230:233], off
	global_store_dwordx4 v[248:249], v[238:241], off offset:256
	v_permlane16_swap_b32_e32 v251, v250
	v_lshl_add_u64 v[248:249], v[248:249], 0, s[38:39]
	s_nop 0
	v_add_f32_e32 v250, v250, v251
	v_mov_b32_e32 v251, v250
	s_nop 1
	v_permlane32_swap_b32_e32 v251, v250
	s_nop 1
	v_add_f32_e32 v250, v250, v251
	s_and_saveexec_b64 s[20:21], s[2:3]
	global_store_dword v[242:243], v250, off
	s_or_b64 exec, exec, s[20:21]
	s_waitcnt vmcnt(15)
	v_lshlrev_b32_e32 v226, 16, v168
	v_and_b32_e32 v227, 0xffff0000, v168
	v_lshlrev_b32_e32 v228, 16, v169
	v_and_b32_e32 v229, 0xffff0000, v169
	v_lshlrev_b32_e32 v230, 16, v170
	v_and_b32_e32 v231, 0xffff0000, v170
	v_lshlrev_b32_e32 v232, 16, v171
	v_and_b32_e32 v233, 0xffff0000, v171
	v_lshlrev_b32_e32 v234, 16, v172
	v_and_b32_e32 v235, 0xffff0000, v172
	v_lshlrev_b32_e32 v236, 16, v173
	v_and_b32_e32 v237, 0xffff0000, v173
	v_lshlrev_b32_e32 v238, 16, v174
	v_and_b32_e32 v239, 0xffff0000, v174
	v_lshlrev_b32_e32 v240, 16, v175
	v_and_b32_e32 v241, 0xffff0000, v175
	v_pk_add_f32 v[108:109], v[108:109], v[226:227]
	v_pk_add_f32 v[110:111], v[110:111], v[228:229]
	v_pk_add_f32 v[104:105], v[104:105], v[230:231]
	v_pk_add_f32 v[106:107], v[106:107], v[232:233]
	v_pk_add_f32 v[100:101], v[100:101], v[234:235]
	v_pk_add_f32 v[102:103], v[102:103], v[236:237]
	v_pk_add_f32 v[96:97], v[96:97], v[238:239]
	v_pk_add_f32 v[98:99], v[98:99], v[240:241]
	v_mul_f32_e32 v226, v109, v109
	v_mul_f32_e32 v227, v111, v111
	v_mul_f32_e32 v228, v105, v105
	v_mul_f32_e32 v229, v107, v107
	v_mul_f32_e32 v234, v101, v101
	v_mul_f32_e32 v235, v103, v103
	v_mul_f32_e32 v236, v97, v97
	v_mul_f32_e32 v237, v99, v99
	v_fmac_f32_e32 v226, v108, v108
	v_fmac_f32_e32 v227, v110, v110
	v_fmac_f32_e32 v228, v104, v104
	v_fmac_f32_e32 v229, v106, v106
	v_fmac_f32_e32 v234, v100, v100
	v_fmac_f32_e32 v235, v102, v102
	v_fmac_f32_e32 v236, v96, v96
	v_fmac_f32_e32 v237, v98, v98
	v_add_f32_e32 v226, v226, v227
	v_add_f32_e32 v234, v234, v235
	v_add_f32_e32 v226, v228, v226
	v_add_f32_e32 v234, v236, v234
	v_add_f32_e32 v226, v229, v226
	v_add_f32_e32 v234, v237, v234
	v_add_f32_e32 v250, v226, v234
	v_cvt_pk_bf16_f32 v230, v108, v109
	v_cvt_pk_bf16_f32 v231, v110, v111
	v_cvt_pk_bf16_f32 v232, v104, v105
	v_cvt_pk_bf16_f32 v233, v106, v107
	v_cvt_pk_bf16_f32 v238, v100, v101
	v_cvt_pk_bf16_f32 v239, v102, v103
	v_cvt_pk_bf16_f32 v240, v96, v97
	v_cvt_pk_bf16_f32 v241, v98, v99
	v_mov_b32_e32 v251, v250
	global_store_dwordx4 v[248:249], v[230:233], off
	global_store_dwordx4 v[248:249], v[238:241], off offset:256
	v_permlane16_swap_b32_e32 v251, v250
	v_lshl_add_u64 v[248:249], v[248:249], 0, s[38:39]
	s_nop 0
	v_add_f32_e32 v250, v250, v251
	v_mov_b32_e32 v251, v250
	s_nop 1
	v_permlane32_swap_b32_e32 v251, v250
	s_nop 1
	v_add_f32_e32 v250, v250, v251
	s_and_saveexec_b64 s[20:21], s[2:3]
	global_store_dword v[242:243], v250, off offset:1024
	s_or_b64 exec, exec, s[20:21]
	s_waitcnt vmcnt(16)
	v_lshlrev_b32_e32 v226, 16, v176
	v_and_b32_e32 v227, 0xffff0000, v176
	v_lshlrev_b32_e32 v228, 16, v177
	v_and_b32_e32 v229, 0xffff0000, v177
	v_lshlrev_b32_e32 v230, 16, v178
	v_and_b32_e32 v231, 0xffff0000, v178
	v_lshlrev_b32_e32 v232, 16, v179
	v_and_b32_e32 v233, 0xffff0000, v179
	v_lshlrev_b32_e32 v234, 16, v180
	v_and_b32_e32 v235, 0xffff0000, v180
	v_lshlrev_b32_e32 v236, 16, v181
	v_and_b32_e32 v237, 0xffff0000, v181
	v_lshlrev_b32_e32 v238, 16, v182
	v_and_b32_e32 v239, 0xffff0000, v182
	v_lshlrev_b32_e32 v240, 16, v183
	v_and_b32_e32 v241, 0xffff0000, v183
	v_pk_add_f32 v[92:93], v[92:93], v[226:227]
	v_pk_add_f32 v[94:95], v[94:95], v[228:229]
	v_pk_add_f32 v[88:89], v[88:89], v[230:231]
	v_pk_add_f32 v[90:91], v[90:91], v[232:233]
	v_pk_add_f32 v[84:85], v[84:85], v[234:235]
	v_pk_add_f32 v[86:87], v[86:87], v[236:237]
	v_pk_add_f32 v[80:81], v[80:81], v[238:239]
	v_pk_add_f32 v[82:83], v[82:83], v[240:241]
	v_mul_f32_e32 v226, v93, v93
	v_mul_f32_e32 v227, v95, v95
	v_mul_f32_e32 v228, v89, v89
	v_mul_f32_e32 v229, v91, v91
	v_mul_f32_e32 v234, v85, v85
	v_mul_f32_e32 v235, v87, v87
	v_mul_f32_e32 v236, v81, v81
	v_mul_f32_e32 v237, v83, v83
	v_fmac_f32_e32 v226, v92, v92
	v_fmac_f32_e32 v227, v94, v94
	v_fmac_f32_e32 v228, v88, v88
	v_fmac_f32_e32 v229, v90, v90
	v_fmac_f32_e32 v234, v84, v84
	v_fmac_f32_e32 v235, v86, v86
	v_fmac_f32_e32 v236, v80, v80
	v_fmac_f32_e32 v237, v82, v82
	v_add_f32_e32 v226, v226, v227
	v_add_f32_e32 v234, v234, v235
	v_add_f32_e32 v226, v228, v226
	v_add_f32_e32 v234, v236, v234
	v_add_f32_e32 v226, v229, v226
	v_add_f32_e32 v234, v237, v234
	v_add_f32_e32 v250, v226, v234
	v_cvt_pk_bf16_f32 v230, v92, v93
	v_cvt_pk_bf16_f32 v231, v94, v95
	v_cvt_pk_bf16_f32 v232, v88, v89
	v_cvt_pk_bf16_f32 v233, v90, v91
	v_cvt_pk_bf16_f32 v238, v84, v85
	v_cvt_pk_bf16_f32 v239, v86, v87
	v_cvt_pk_bf16_f32 v240, v80, v81
	v_cvt_pk_bf16_f32 v241, v82, v83
	v_mov_b32_e32 v251, v250
	global_store_dwordx4 v[248:249], v[230:233], off
	global_store_dwordx4 v[248:249], v[238:241], off offset:256
	v_permlane16_swap_b32_e32 v251, v250
	v_lshl_add_u64 v[248:249], v[248:249], 0, s[38:39]
	s_nop 0
	v_add_f32_e32 v250, v250, v251
	v_mov_b32_e32 v251, v250
	s_nop 1
	v_permlane32_swap_b32_e32 v251, v250
	s_nop 1
	v_add_f32_e32 v250, v250, v251
	s_and_saveexec_b64 s[20:21], s[2:3]
	global_store_dword v[242:243], v250, off offset:2048
	s_or_b64 exec, exec, s[20:21]
	s_waitcnt vmcnt(17)
	v_lshlrev_b32_e32 v226, 16, v184
	v_and_b32_e32 v227, 0xffff0000, v184
	v_lshlrev_b32_e32 v228, 16, v185
	v_and_b32_e32 v229, 0xffff0000, v185
	v_lshlrev_b32_e32 v230, 16, v186
	v_and_b32_e32 v231, 0xffff0000, v186
	v_lshlrev_b32_e32 v232, 16, v187
	v_and_b32_e32 v233, 0xffff0000, v187
	v_lshlrev_b32_e32 v234, 16, v188
	v_and_b32_e32 v235, 0xffff0000, v188
	v_lshlrev_b32_e32 v236, 16, v189
	v_and_b32_e32 v237, 0xffff0000, v189
	v_lshlrev_b32_e32 v238, 16, v190
	v_and_b32_e32 v239, 0xffff0000, v190
	v_lshlrev_b32_e32 v240, 16, v191
	v_and_b32_e32 v241, 0xffff0000, v191
	v_pk_add_f32 v[76:77], v[76:77], v[226:227]
	v_pk_add_f32 v[78:79], v[78:79], v[228:229]
	v_pk_add_f32 v[72:73], v[72:73], v[230:231]
	v_pk_add_f32 v[74:75], v[74:75], v[232:233]
	v_pk_add_f32 v[68:69], v[68:69], v[234:235]
	v_pk_add_f32 v[70:71], v[70:71], v[236:237]
	v_pk_add_f32 v[64:65], v[64:65], v[238:239]
	v_pk_add_f32 v[66:67], v[66:67], v[240:241]
	v_mul_f32_e32 v226, v77, v77
	v_mul_f32_e32 v227, v79, v79
	v_mul_f32_e32 v228, v73, v73
	v_mul_f32_e32 v229, v75, v75
	v_mul_f32_e32 v234, v69, v69
	v_mul_f32_e32 v235, v71, v71
	v_mul_f32_e32 v236, v65, v65
	v_mul_f32_e32 v237, v67, v67
	v_fmac_f32_e32 v226, v76, v76
	v_fmac_f32_e32 v227, v78, v78
	v_fmac_f32_e32 v228, v72, v72
	v_fmac_f32_e32 v229, v74, v74
	v_fmac_f32_e32 v234, v68, v68
	v_fmac_f32_e32 v235, v70, v70
	v_fmac_f32_e32 v236, v64, v64
	v_fmac_f32_e32 v237, v66, v66
	v_add_f32_e32 v226, v226, v227
	v_add_f32_e32 v234, v234, v235
	v_add_f32_e32 v226, v228, v226
	v_add_f32_e32 v234, v236, v234
	v_add_f32_e32 v226, v229, v226
	v_add_f32_e32 v234, v237, v234
	v_add_f32_e32 v250, v226, v234
	v_cvt_pk_bf16_f32 v230, v76, v77
	v_cvt_pk_bf16_f32 v231, v78, v79
	v_cvt_pk_bf16_f32 v232, v72, v73
	v_cvt_pk_bf16_f32 v233, v74, v75
	v_cvt_pk_bf16_f32 v238, v68, v69
	v_cvt_pk_bf16_f32 v239, v70, v71
	v_cvt_pk_bf16_f32 v240, v64, v65
	v_cvt_pk_bf16_f32 v241, v66, v67
	v_mov_b32_e32 v251, v250
	global_store_dwordx4 v[248:249], v[230:233], off
	global_store_dwordx4 v[248:249], v[238:241], off offset:256
	v_permlane16_swap_b32_e32 v251, v250
	v_lshl_add_u64 v[248:249], v[248:249], 0, s[6:7]
	s_nop 0
	v_add_f32_e32 v250, v250, v251
	v_mov_b32_e32 v251, v250
	s_nop 1
	v_permlane32_swap_b32_e32 v251, v250
	s_nop 1
	v_add_f32_e32 v250, v250, v251
	s_and_saveexec_b64 s[20:21], s[2:3]
	global_store_dword v[242:243], v250, off offset:3072
	s_or_b64 exec, exec, s[20:21]
	s_waitcnt vmcnt(18)
	v_lshlrev_b32_e32 v226, 16, v192
	v_and_b32_e32 v227, 0xffff0000, v192
	v_lshlrev_b32_e32 v228, 16, v193
	v_and_b32_e32 v229, 0xffff0000, v193
	v_lshlrev_b32_e32 v230, 16, v194
	v_and_b32_e32 v231, 0xffff0000, v194
	v_lshlrev_b32_e32 v232, 16, v195
	v_and_b32_e32 v233, 0xffff0000, v195
	v_lshlrev_b32_e32 v234, 16, v196
	v_and_b32_e32 v235, 0xffff0000, v196
	v_lshlrev_b32_e32 v236, 16, v197
	v_and_b32_e32 v237, 0xffff0000, v197
	v_lshlrev_b32_e32 v238, 16, v198
	v_and_b32_e32 v239, 0xffff0000, v198
	v_lshlrev_b32_e32 v240, 16, v199
	v_and_b32_e32 v241, 0xffff0000, v199
	v_pk_add_f32 v[60:61], v[60:61], v[226:227]
	v_pk_add_f32 v[62:63], v[62:63], v[228:229]
	v_pk_add_f32 v[56:57], v[56:57], v[230:231]
	v_pk_add_f32 v[58:59], v[58:59], v[232:233]
	v_pk_add_f32 v[52:53], v[52:53], v[234:235]
	v_pk_add_f32 v[54:55], v[54:55], v[236:237]
	v_pk_add_f32 v[48:49], v[48:49], v[238:239]
	v_pk_add_f32 v[50:51], v[50:51], v[240:241]
	v_mul_f32_e32 v226, v61, v61
	v_mul_f32_e32 v227, v63, v63
	v_mul_f32_e32 v228, v57, v57
	v_mul_f32_e32 v229, v59, v59
	v_mul_f32_e32 v234, v53, v53
	v_mul_f32_e32 v235, v55, v55
	v_mul_f32_e32 v236, v49, v49
	v_mul_f32_e32 v237, v51, v51
	v_fmac_f32_e32 v226, v60, v60
	v_fmac_f32_e32 v227, v62, v62
	v_fmac_f32_e32 v228, v56, v56
	v_fmac_f32_e32 v229, v58, v58
	v_fmac_f32_e32 v234, v52, v52
	v_fmac_f32_e32 v235, v54, v54
	v_fmac_f32_e32 v236, v48, v48
	v_fmac_f32_e32 v237, v50, v50
	v_add_f32_e32 v226, v226, v227
	v_add_f32_e32 v234, v234, v235
	v_add_f32_e32 v226, v228, v226
	v_add_f32_e32 v234, v236, v234
	v_add_f32_e32 v226, v229, v226
	v_add_f32_e32 v234, v237, v234
	v_add_f32_e32 v250, v226, v234
	v_cvt_pk_bf16_f32 v230, v60, v61
	v_cvt_pk_bf16_f32 v231, v62, v63
	v_cvt_pk_bf16_f32 v232, v56, v57
	v_cvt_pk_bf16_f32 v233, v58, v59
	v_cvt_pk_bf16_f32 v238, v52, v53
	v_cvt_pk_bf16_f32 v239, v54, v55
	v_cvt_pk_bf16_f32 v240, v48, v49
	v_cvt_pk_bf16_f32 v241, v50, v51
	v_mov_b32_e32 v251, v250
	global_store_dwordx4 v[248:249], v[230:233], off
	global_store_dwordx4 v[248:249], v[238:241], off offset:256
	v_permlane16_swap_b32_e32 v251, v250
	v_lshl_add_u64 v[248:249], v[248:249], 0, s[38:39]
	s_nop 0
	v_add_f32_e32 v250, v250, v251
	v_mov_b32_e32 v251, v250
	s_nop 1
	v_permlane32_swap_b32_e32 v251, v250
	s_nop 1
	v_add_f32_e32 v250, v250, v251
	s_and_saveexec_b64 s[20:21], s[2:3]
	global_store_dword v[244:245], v250, off
	s_or_b64 exec, exec, s[20:21]
	s_waitcnt vmcnt(19)
	v_lshlrev_b32_e32 v226, 16, v200
	v_and_b32_e32 v227, 0xffff0000, v200
	v_lshlrev_b32_e32 v228, 16, v201
	v_and_b32_e32 v229, 0xffff0000, v201
	v_lshlrev_b32_e32 v230, 16, v202
	v_and_b32_e32 v231, 0xffff0000, v202
	v_lshlrev_b32_e32 v232, 16, v203
	v_and_b32_e32 v233, 0xffff0000, v203
	v_lshlrev_b32_e32 v234, 16, v204
	v_and_b32_e32 v235, 0xffff0000, v204
	v_lshlrev_b32_e32 v236, 16, v205
	v_and_b32_e32 v237, 0xffff0000, v205
	v_lshlrev_b32_e32 v238, 16, v206
	v_and_b32_e32 v239, 0xffff0000, v206
	v_lshlrev_b32_e32 v240, 16, v207
	v_and_b32_e32 v241, 0xffff0000, v207
	v_pk_add_f32 v[44:45], v[44:45], v[226:227]
	v_pk_add_f32 v[46:47], v[46:47], v[228:229]
	v_pk_add_f32 v[40:41], v[40:41], v[230:231]
	v_pk_add_f32 v[42:43], v[42:43], v[232:233]
	v_pk_add_f32 v[36:37], v[36:37], v[234:235]
	v_pk_add_f32 v[38:39], v[38:39], v[236:237]
	v_pk_add_f32 v[32:33], v[32:33], v[238:239]
	v_pk_add_f32 v[34:35], v[34:35], v[240:241]
	v_mul_f32_e32 v226, v45, v45
	v_mul_f32_e32 v227, v47, v47
	v_mul_f32_e32 v228, v41, v41
	v_mul_f32_e32 v229, v43, v43
	v_mul_f32_e32 v234, v37, v37
	v_mul_f32_e32 v235, v39, v39
	v_mul_f32_e32 v236, v33, v33
	v_mul_f32_e32 v237, v35, v35
	v_fmac_f32_e32 v226, v44, v44
	v_fmac_f32_e32 v227, v46, v46
	v_fmac_f32_e32 v228, v40, v40
	v_fmac_f32_e32 v229, v42, v42
	v_fmac_f32_e32 v234, v36, v36
	v_fmac_f32_e32 v235, v38, v38
	v_fmac_f32_e32 v236, v32, v32
	v_fmac_f32_e32 v237, v34, v34
	v_add_f32_e32 v226, v226, v227
	v_add_f32_e32 v234, v234, v235
	v_add_f32_e32 v226, v228, v226
	v_add_f32_e32 v234, v236, v234
	v_add_f32_e32 v226, v229, v226
	v_add_f32_e32 v234, v237, v234
	v_add_f32_e32 v250, v226, v234
	v_cvt_pk_bf16_f32 v230, v44, v45
	v_cvt_pk_bf16_f32 v231, v46, v47
	v_cvt_pk_bf16_f32 v232, v40, v41
	v_cvt_pk_bf16_f32 v233, v42, v43
	v_cvt_pk_bf16_f32 v238, v36, v37
	v_cvt_pk_bf16_f32 v239, v38, v39
	v_cvt_pk_bf16_f32 v240, v32, v33
	v_cvt_pk_bf16_f32 v241, v34, v35
	v_mov_b32_e32 v251, v250
	global_store_dwordx4 v[248:249], v[230:233], off
	global_store_dwordx4 v[248:249], v[238:241], off offset:256
	v_permlane16_swap_b32_e32 v251, v250
	v_lshl_add_u64 v[248:249], v[248:249], 0, s[38:39]
	s_nop 0
	v_add_f32_e32 v250, v250, v251
	v_mov_b32_e32 v251, v250
	s_nop 1
	v_permlane32_swap_b32_e32 v251, v250
	s_nop 1
	v_add_f32_e32 v250, v250, v251
	s_and_saveexec_b64 s[20:21], s[2:3]
	global_store_dword v[244:245], v250, off offset:1024
	s_or_b64 exec, exec, s[20:21]
	s_waitcnt vmcnt(20)
	v_lshlrev_b32_e32 v226, 16, v208
	v_and_b32_e32 v227, 0xffff0000, v208
	v_lshlrev_b32_e32 v228, 16, v209
	v_and_b32_e32 v229, 0xffff0000, v209
	v_lshlrev_b32_e32 v230, 16, v210
	v_and_b32_e32 v231, 0xffff0000, v210
	v_lshlrev_b32_e32 v232, 16, v211
	v_and_b32_e32 v233, 0xffff0000, v211
	v_lshlrev_b32_e32 v234, 16, v212
	v_and_b32_e32 v235, 0xffff0000, v212
	v_lshlrev_b32_e32 v236, 16, v213
	v_and_b32_e32 v237, 0xffff0000, v213
	v_lshlrev_b32_e32 v238, 16, v214
	v_and_b32_e32 v239, 0xffff0000, v214
	v_lshlrev_b32_e32 v240, 16, v215
	v_and_b32_e32 v241, 0xffff0000, v215
	v_pk_add_f32 v[28:29], v[28:29], v[226:227]
	v_pk_add_f32 v[30:31], v[30:31], v[228:229]
	v_pk_add_f32 v[24:25], v[24:25], v[230:231]
	v_pk_add_f32 v[26:27], v[26:27], v[232:233]
	v_pk_add_f32 v[20:21], v[20:21], v[234:235]
	v_pk_add_f32 v[22:23], v[22:23], v[236:237]
	v_pk_add_f32 v[16:17], v[16:17], v[238:239]
	v_pk_add_f32 v[18:19], v[18:19], v[240:241]
	v_mul_f32_e32 v226, v29, v29
	v_mul_f32_e32 v227, v31, v31
	v_mul_f32_e32 v228, v25, v25
	v_mul_f32_e32 v229, v27, v27
	v_mul_f32_e32 v234, v21, v21
	v_mul_f32_e32 v235, v23, v23
	v_mul_f32_e32 v236, v17, v17
	v_mul_f32_e32 v237, v19, v19
	v_fmac_f32_e32 v226, v28, v28
	v_fmac_f32_e32 v227, v30, v30
	v_fmac_f32_e32 v228, v24, v24
	v_fmac_f32_e32 v229, v26, v26
	v_fmac_f32_e32 v234, v20, v20
	v_fmac_f32_e32 v235, v22, v22
	v_fmac_f32_e32 v236, v16, v16
	v_fmac_f32_e32 v237, v18, v18
	v_add_f32_e32 v226, v226, v227
	v_add_f32_e32 v234, v234, v235
	v_add_f32_e32 v226, v228, v226
	v_add_f32_e32 v234, v236, v234
	v_add_f32_e32 v226, v229, v226
	v_add_f32_e32 v234, v237, v234
	v_add_f32_e32 v250, v226, v234
	v_cvt_pk_bf16_f32 v230, v28, v29
	v_cvt_pk_bf16_f32 v231, v30, v31
	v_cvt_pk_bf16_f32 v232, v24, v25
	v_cvt_pk_bf16_f32 v233, v26, v27
	v_cvt_pk_bf16_f32 v238, v20, v21
	v_cvt_pk_bf16_f32 v239, v22, v23
	v_cvt_pk_bf16_f32 v240, v16, v17
	v_cvt_pk_bf16_f32 v241, v18, v19
	v_mov_b32_e32 v251, v250
	global_store_dwordx4 v[248:249], v[230:233], off
	global_store_dwordx4 v[248:249], v[238:241], off offset:256
	v_permlane16_swap_b32_e32 v251, v250
	v_lshl_add_u64 v[248:249], v[248:249], 0, s[38:39]
	s_nop 0
	v_add_f32_e32 v250, v250, v251
	v_mov_b32_e32 v251, v250
	s_nop 1
	v_permlane32_swap_b32_e32 v251, v250
	s_nop 1
	v_add_f32_e32 v250, v250, v251
	s_and_saveexec_b64 s[20:21], s[2:3]
	global_store_dword v[244:245], v250, off offset:2048
	s_or_b64 exec, exec, s[20:21]
	s_waitcnt vmcnt(21)
	v_lshlrev_b32_e32 v226, 16, v216
	v_and_b32_e32 v227, 0xffff0000, v216
	v_lshlrev_b32_e32 v228, 16, v217
	v_and_b32_e32 v229, 0xffff0000, v217
	v_lshlrev_b32_e32 v230, 16, v218
	v_and_b32_e32 v231, 0xffff0000, v218
	v_lshlrev_b32_e32 v232, 16, v219
	v_and_b32_e32 v233, 0xffff0000, v219
	v_lshlrev_b32_e32 v234, 16, v220
	v_and_b32_e32 v235, 0xffff0000, v220
	v_lshlrev_b32_e32 v236, 16, v221
	v_and_b32_e32 v237, 0xffff0000, v221
	v_lshlrev_b32_e32 v238, 16, v222
	v_and_b32_e32 v239, 0xffff0000, v222
	v_lshlrev_b32_e32 v240, 16, v223
	v_and_b32_e32 v241, 0xffff0000, v223
	v_pk_add_f32 v[12:13], v[12:13], v[226:227]
	v_pk_add_f32 v[14:15], v[14:15], v[228:229]
	v_pk_add_f32 v[8:9], v[8:9], v[230:231]
	v_pk_add_f32 v[10:11], v[10:11], v[232:233]
	v_pk_add_f32 v[4:5], v[4:5], v[234:235]
	v_pk_add_f32 v[6:7], v[6:7], v[236:237]
	v_pk_add_f32 v[0:1], v[0:1], v[238:239]
	v_pk_add_f32 v[2:3], v[2:3], v[240:241]
	v_mul_f32_e32 v226, v13, v13
	v_mul_f32_e32 v227, v15, v15
	v_mul_f32_e32 v228, v9, v9
	v_mul_f32_e32 v229, v11, v11
	v_mul_f32_e32 v234, v5, v5
	v_mul_f32_e32 v235, v7, v7
	v_mul_f32_e32 v236, v1, v1
	v_mul_f32_e32 v237, v3, v3
	v_fmac_f32_e32 v226, v12, v12
	v_fmac_f32_e32 v227, v14, v14
	v_fmac_f32_e32 v228, v8, v8
	v_fmac_f32_e32 v229, v10, v10
	v_fmac_f32_e32 v234, v4, v4
	v_fmac_f32_e32 v235, v6, v6
	v_fmac_f32_e32 v236, v0, v0
	v_fmac_f32_e32 v237, v2, v2
	v_add_f32_e32 v226, v226, v227
	v_add_f32_e32 v234, v234, v235
	v_add_f32_e32 v226, v228, v226
	v_add_f32_e32 v234, v236, v234
	v_add_f32_e32 v226, v229, v226
	v_add_f32_e32 v234, v237, v234
	v_add_f32_e32 v250, v226, v234
	v_cvt_pk_bf16_f32 v230, v12, v13
	v_cvt_pk_bf16_f32 v231, v14, v15
	v_cvt_pk_bf16_f32 v232, v8, v9
	v_cvt_pk_bf16_f32 v233, v10, v11
	v_cvt_pk_bf16_f32 v238, v4, v5
	v_cvt_pk_bf16_f32 v239, v6, v7
	v_cvt_pk_bf16_f32 v240, v0, v1
	v_cvt_pk_bf16_f32 v241, v2, v3
	v_mov_b32_e32 v251, v250
	global_store_dwordx4 v[248:249], v[230:233], off
	global_store_dwordx4 v[248:249], v[238:241], off offset:256
	v_permlane16_swap_b32_e32 v251, v250
	s_nop 0
	s_nop 0
	v_add_f32_e32 v250, v250, v251
	v_mov_b32_e32 v251, v250
	s_nop 1
	v_permlane32_swap_b32_e32 v251, v250
	s_nop 1
	v_add_f32_e32 v250, v250, v251
	s_and_saveexec_b64 s[20:21], s[2:3]
	global_store_dword v[244:245], v250, off offset:3072
	s_or_b64 exec, exec, s[20:21]
	s_andn2_b64 vcc, exec, s[4:5]
	s_mov_b64 s[4:5], -1
	s_cbranch_vccnz .LBB0_681
	s_andn2_b64 vcc, exec, s[8:9]
	s_cbranch_vccnz .LBB0_680
	s_barrier
	s_branch .LBB0_680

.LBB0_911:
	v_lshl_add_u32 v146, s52, 8, v148
	v_mov_b32_e32 v147, 0
	v_lshl_add_u32 v144, s8, 8, v150
	v_mov_b32_e32 v145, 0
	v_lshlrev_b64 v[156:157], 11, v[146:147]
	v_lshl_add_u64 v[156:157], s[12:13], 0, v[156:157]
	v_lshl_add_u64 v[246:247], v[144:145], 1, v[156:157]
	v_mov_b32_e32 v248, v246
	v_mov_b32_e32 v249, v247
	v_lshlrev_b64 v[156:157], 6, v[146:147]
	v_lshl_add_u64 v[242:243], s[14:15], 0, v[156:157]
	s_lshl_b32 s28, s8, 2
	s_add_i32 s28, s28, s41
	s_lshl_b32 s28, s28, 2
	s_mov_b32 s29, 0
	v_lshl_add_u64 v[242:243], v[242:243], 0, s[28:29]
	s_mov_b64 s[8:9], 0x2000
	v_lshl_add_u64 v[244:245], v[242:243], 0, s[8:9]
	s_mov_b64 s[28:29], 0x8000
	s_mov_b64 s[8:9], 0x28000
	global_load_dwordx4 v[160:163], v[246:247], off
	global_load_dwordx4 v[164:167], v[246:247], off offset:256
	v_lshl_add_u64 v[246:247], v[246:247], 0, s[28:29]
	global_load_dwordx4 v[168:171], v[246:247], off
	global_load_dwordx4 v[172:175], v[246:247], off offset:256
	v_lshl_add_u64 v[246:247], v[246:247], 0, s[28:29]
	global_load_dwordx4 v[176:179], v[246:247], off
	global_load_dwordx4 v[180:183], v[246:247], off offset:256
	v_lshl_add_u64 v[246:247], v[246:247], 0, s[28:29]
	global_load_dwordx4 v[184:187], v[246:247], off
	global_load_dwordx4 v[188:191], v[246:247], off offset:256
	v_lshl_add_u64 v[246:247], v[246:247], 0, s[8:9]
	global_load_dwordx4 v[192:195], v[246:247], off
	global_load_dwordx4 v[196:199], v[246:247], off offset:256
	v_lshl_add_u64 v[246:247], v[246:247], 0, s[28:29]
	global_load_dwordx4 v[200:203], v[246:247], off
	global_load_dwordx4 v[204:207], v[246:247], off offset:256
	v_lshl_add_u64 v[246:247], v[246:247], 0, s[28:29]
	global_load_dwordx4 v[208:211], v[246:247], off
	global_load_dwordx4 v[212:215], v[246:247], off offset:256
	v_lshl_add_u64 v[246:247], v[246:247], 0, s[28:29]
	global_load_dwordx4 v[216:219], v[246:247], off
	global_load_dwordx4 v[220:223], v[246:247], off offset:256
	s_waitcnt vmcnt(14)
	v_lshlrev_b32_e32 v226, 16, v160
	v_and_b32_e32 v227, 0xffff0000, v160
	v_lshlrev_b32_e32 v228, 16, v161
	v_and_b32_e32 v229, 0xffff0000, v161
	v_lshlrev_b32_e32 v230, 16, v162
	v_and_b32_e32 v231, 0xffff0000, v162
	v_lshlrev_b32_e32 v232, 16, v163
	v_and_b32_e32 v233, 0xffff0000, v163
	v_lshlrev_b32_e32 v234, 16, v164
	v_and_b32_e32 v235, 0xffff0000, v164
	v_lshlrev_b32_e32 v236, 16, v165
	v_and_b32_e32 v237, 0xffff0000, v165
	v_lshlrev_b32_e32 v238, 16, v166
	v_and_b32_e32 v239, 0xffff0000, v166
	v_lshlrev_b32_e32 v240, 16, v167
	v_and_b32_e32 v241, 0xffff0000, v167
	v_pk_add_f32 v[124:125], v[124:125], v[226:227]
	v_pk_add_f32 v[126:127], v[126:127], v[228:229]
	v_pk_add_f32 v[120:121], v[120:121], v[230:231]
	v_pk_add_f32 v[122:123], v[122:123], v[232:233]
	v_pk_add_f32 v[116:117], v[116:117], v[234:235]
	v_pk_add_f32 v[118:119], v[118:119], v[236:237]
	v_pk_add_f32 v[112:113], v[112:113], v[238:239]
	v_pk_add_f32 v[114:115], v[114:115], v[240:241]
	v_mul_f32_e32 v226, v125, v125
	v_mul_f32_e32 v227, v127, v127
	v_mul_f32_e32 v228, v121, v121
	v_mul_f32_e32 v229, v123, v123
	v_mul_f32_e32 v234, v117, v117
	v_mul_f32_e32 v235, v119, v119
	v_mul_f32_e32 v236, v113, v113
	v_mul_f32_e32 v237, v115, v115
	v_fmac_f32_e32 v226, v124, v124
	v_fmac_f32_e32 v227, v126, v126
	v_fmac_f32_e32 v228, v120, v120
	v_fmac_f32_e32 v229, v122, v122
	v_fmac_f32_e32 v234, v116, v116
	v_fmac_f32_e32 v235, v118, v118
	v_fmac_f32_e32 v236, v112, v112
	v_fmac_f32_e32 v237, v114, v114
	v_add_f32_e32 v226, v226, v227
	v_add_f32_e32 v234, v234, v235
	v_add_f32_e32 v226, v228, v226
	v_add_f32_e32 v234, v236, v234
	v_add_f32_e32 v226, v229, v226
	v_add_f32_e32 v234, v237, v234
	v_add_f32_e32 v250, v226, v234
	v_cvt_pk_bf16_f32 v230, v124, v125
	v_cvt_pk_bf16_f32 v231, v126, v127
	v_cvt_pk_bf16_f32 v232, v120, v121
	v_cvt_pk_bf16_f32 v233, v122, v123
	v_cvt_pk_bf16_f32 v238, v116, v117
	v_cvt_pk_bf16_f32 v239, v118, v119
	v_cvt_pk_bf16_f32 v240, v112, v113
	v_cvt_pk_bf16_f32 v241, v114, v115
	v_mov_b32_e32 v251, v250
	global_store_dwordx4 v[248:249], v[230:233], off
	global_store_dwordx4 v[248:249], v[238:241], off offset:256
	v_permlane16_swap_b32_e32 v251, v250
	v_lshl_add_u64 v[248:249], v[248:249], 0, s[28:29]
	s_nop 0
	v_add_f32_e32 v250, v250, v251
	v_mov_b32_e32 v251, v250
	s_nop 1
	v_permlane32_swap_b32_e32 v251, v250
	s_nop 1
	v_add_f32_e32 v250, v250, v251
	s_and_saveexec_b64 s[20:21], s[2:3]
	global_store_dword v[242:243], v250, off
	s_or_b64 exec, exec, s[20:21]
	s_waitcnt vmcnt(15)
	v_lshlrev_b32_e32 v226, 16, v168
	v_and_b32_e32 v227, 0xffff0000, v168
	v_lshlrev_b32_e32 v228, 16, v169
	v_and_b32_e32 v229, 0xffff0000, v169
	v_lshlrev_b32_e32 v230, 16, v170
	v_and_b32_e32 v231, 0xffff0000, v170
	v_lshlrev_b32_e32 v232, 16, v171
	v_and_b32_e32 v233, 0xffff0000, v171
	v_lshlrev_b32_e32 v234, 16, v172
	v_and_b32_e32 v235, 0xffff0000, v172
	v_lshlrev_b32_e32 v236, 16, v173
	v_and_b32_e32 v237, 0xffff0000, v173
	v_lshlrev_b32_e32 v238, 16, v174
	v_and_b32_e32 v239, 0xffff0000, v174
	v_lshlrev_b32_e32 v240, 16, v175
	v_and_b32_e32 v241, 0xffff0000, v175
	v_pk_add_f32 v[108:109], v[108:109], v[226:227]
	v_pk_add_f32 v[110:111], v[110:111], v[228:229]
	v_pk_add_f32 v[104:105], v[104:105], v[230:231]
	v_pk_add_f32 v[106:107], v[106:107], v[232:233]
	v_pk_add_f32 v[100:101], v[100:101], v[234:235]
	v_pk_add_f32 v[102:103], v[102:103], v[236:237]
	v_pk_add_f32 v[96:97], v[96:97], v[238:239]
	v_pk_add_f32 v[98:99], v[98:99], v[240:241]
	v_mul_f32_e32 v226, v109, v109
	v_mul_f32_e32 v227, v111, v111
	v_mul_f32_e32 v228, v105, v105
	v_mul_f32_e32 v229, v107, v107
	v_mul_f32_e32 v234, v101, v101
	v_mul_f32_e32 v235, v103, v103
	v_mul_f32_e32 v236, v97, v97
	v_mul_f32_e32 v237, v99, v99
	v_fmac_f32_e32 v226, v108, v108
	v_fmac_f32_e32 v227, v110, v110
	v_fmac_f32_e32 v228, v104, v104
	v_fmac_f32_e32 v229, v106, v106
	v_fmac_f32_e32 v234, v100, v100
	v_fmac_f32_e32 v235, v102, v102
	v_fmac_f32_e32 v236, v96, v96
	v_fmac_f32_e32 v237, v98, v98
	v_add_f32_e32 v226, v226, v227
	v_add_f32_e32 v234, v234, v235
	v_add_f32_e32 v226, v228, v226
	v_add_f32_e32 v234, v236, v234
	v_add_f32_e32 v226, v229, v226
	v_add_f32_e32 v234, v237, v234
	v_add_f32_e32 v250, v226, v234
	v_cvt_pk_bf16_f32 v230, v108, v109
	v_cvt_pk_bf16_f32 v231, v110, v111
	v_cvt_pk_bf16_f32 v232, v104, v105
	v_cvt_pk_bf16_f32 v233, v106, v107
	v_cvt_pk_bf16_f32 v238, v100, v101
	v_cvt_pk_bf16_f32 v239, v102, v103
	v_cvt_pk_bf16_f32 v240, v96, v97
	v_cvt_pk_bf16_f32 v241, v98, v99
	v_mov_b32_e32 v251, v250
	global_store_dwordx4 v[248:249], v[230:233], off
	global_store_dwordx4 v[248:249], v[238:241], off offset:256
	v_permlane16_swap_b32_e32 v251, v250
	v_lshl_add_u64 v[248:249], v[248:249], 0, s[28:29]
	s_nop 0
	v_add_f32_e32 v250, v250, v251
	v_mov_b32_e32 v251, v250
	s_nop 1
	v_permlane32_swap_b32_e32 v251, v250
	s_nop 1
	v_add_f32_e32 v250, v250, v251
	s_and_saveexec_b64 s[20:21], s[2:3]
	global_store_dword v[242:243], v250, off offset:1024
	s_or_b64 exec, exec, s[20:21]
	s_waitcnt vmcnt(16)
	v_lshlrev_b32_e32 v226, 16, v176
	v_and_b32_e32 v227, 0xffff0000, v176
	v_lshlrev_b32_e32 v228, 16, v177
	v_and_b32_e32 v229, 0xffff0000, v177
	v_lshlrev_b32_e32 v230, 16, v178
	v_and_b32_e32 v231, 0xffff0000, v178
	v_lshlrev_b32_e32 v232, 16, v179
	v_and_b32_e32 v233, 0xffff0000, v179
	v_lshlrev_b32_e32 v234, 16, v180
	v_and_b32_e32 v235, 0xffff0000, v180
	v_lshlrev_b32_e32 v236, 16, v181
	v_and_b32_e32 v237, 0xffff0000, v181
	v_lshlrev_b32_e32 v238, 16, v182
	v_and_b32_e32 v239, 0xffff0000, v182
	v_lshlrev_b32_e32 v240, 16, v183
	v_and_b32_e32 v241, 0xffff0000, v183
	v_pk_add_f32 v[92:93], v[92:93], v[226:227]
	v_pk_add_f32 v[94:95], v[94:95], v[228:229]
	v_pk_add_f32 v[88:89], v[88:89], v[230:231]
	v_pk_add_f32 v[90:91], v[90:91], v[232:233]
	v_pk_add_f32 v[84:85], v[84:85], v[234:235]
	v_pk_add_f32 v[86:87], v[86:87], v[236:237]
	v_pk_add_f32 v[80:81], v[80:81], v[238:239]
	v_pk_add_f32 v[82:83], v[82:83], v[240:241]
	v_mul_f32_e32 v226, v93, v93
	v_mul_f32_e32 v227, v95, v95
	v_mul_f32_e32 v228, v89, v89
	v_mul_f32_e32 v229, v91, v91
	v_mul_f32_e32 v234, v85, v85
	v_mul_f32_e32 v235, v87, v87
	v_mul_f32_e32 v236, v81, v81
	v_mul_f32_e32 v237, v83, v83
	v_fmac_f32_e32 v226, v92, v92
	v_fmac_f32_e32 v227, v94, v94
	v_fmac_f32_e32 v228, v88, v88
	v_fmac_f32_e32 v229, v90, v90
	v_fmac_f32_e32 v234, v84, v84
	v_fmac_f32_e32 v235, v86, v86
	v_fmac_f32_e32 v236, v80, v80
	v_fmac_f32_e32 v237, v82, v82
	v_add_f32_e32 v226, v226, v227
	v_add_f32_e32 v234, v234, v235
	v_add_f32_e32 v226, v228, v226
	v_add_f32_e32 v234, v236, v234
	v_add_f32_e32 v226, v229, v226
	v_add_f32_e32 v234, v237, v234
	v_add_f32_e32 v250, v226, v234
	v_cvt_pk_bf16_f32 v230, v92, v93
	v_cvt_pk_bf16_f32 v231, v94, v95
	v_cvt_pk_bf16_f32 v232, v88, v89
	v_cvt_pk_bf16_f32 v233, v90, v91
	v_cvt_pk_bf16_f32 v238, v84, v85
	v_cvt_pk_bf16_f32 v239, v86, v87
	v_cvt_pk_bf16_f32 v240, v80, v81
	v_cvt_pk_bf16_f32 v241, v82, v83
	v_mov_b32_e32 v251, v250
	global_store_dwordx4 v[248:249], v[230:233], off
	global_store_dwordx4 v[248:249], v[238:241], off offset:256
	v_permlane16_swap_b32_e32 v251, v250
	v_lshl_add_u64 v[248:249], v[248:249], 0, s[28:29]
	s_nop 0
	v_add_f32_e32 v250, v250, v251
	v_mov_b32_e32 v251, v250
	s_nop 1
	v_permlane32_swap_b32_e32 v251, v250
	s_nop 1
	v_add_f32_e32 v250, v250, v251
	s_and_saveexec_b64 s[20:21], s[2:3]
	global_store_dword v[242:243], v250, off offset:2048
	s_or_b64 exec, exec, s[20:21]
	s_waitcnt vmcnt(17)
	v_lshlrev_b32_e32 v226, 16, v184
	v_and_b32_e32 v227, 0xffff0000, v184
	v_lshlrev_b32_e32 v228, 16, v185
	v_and_b32_e32 v229, 0xffff0000, v185
	v_lshlrev_b32_e32 v230, 16, v186
	v_and_b32_e32 v231, 0xffff0000, v186
	v_lshlrev_b32_e32 v232, 16, v187
	v_and_b32_e32 v233, 0xffff0000, v187
	v_lshlrev_b32_e32 v234, 16, v188
	v_and_b32_e32 v235, 0xffff0000, v188
	v_lshlrev_b32_e32 v236, 16, v189
	v_and_b32_e32 v237, 0xffff0000, v189
	v_lshlrev_b32_e32 v238, 16, v190
	v_and_b32_e32 v239, 0xffff0000, v190
	v_lshlrev_b32_e32 v240, 16, v191
	v_and_b32_e32 v241, 0xffff0000, v191
	v_pk_add_f32 v[76:77], v[76:77], v[226:227]
	v_pk_add_f32 v[78:79], v[78:79], v[228:229]
	v_pk_add_f32 v[72:73], v[72:73], v[230:231]
	v_pk_add_f32 v[74:75], v[74:75], v[232:233]
	v_pk_add_f32 v[68:69], v[68:69], v[234:235]
	v_pk_add_f32 v[70:71], v[70:71], v[236:237]
	v_pk_add_f32 v[64:65], v[64:65], v[238:239]
	v_pk_add_f32 v[66:67], v[66:67], v[240:241]
	v_mul_f32_e32 v226, v77, v77
	v_mul_f32_e32 v227, v79, v79
	v_mul_f32_e32 v228, v73, v73
	v_mul_f32_e32 v229, v75, v75
	v_mul_f32_e32 v234, v69, v69
	v_mul_f32_e32 v235, v71, v71
	v_mul_f32_e32 v236, v65, v65
	v_mul_f32_e32 v237, v67, v67
	v_fmac_f32_e32 v226, v76, v76
	v_fmac_f32_e32 v227, v78, v78
	v_fmac_f32_e32 v228, v72, v72
	v_fmac_f32_e32 v229, v74, v74
	v_fmac_f32_e32 v234, v68, v68
	v_fmac_f32_e32 v235, v70, v70
	v_fmac_f32_e32 v236, v64, v64
	v_fmac_f32_e32 v237, v66, v66
	v_add_f32_e32 v226, v226, v227
	v_add_f32_e32 v234, v234, v235
	v_add_f32_e32 v226, v228, v226
	v_add_f32_e32 v234, v236, v234
	v_add_f32_e32 v226, v229, v226
	v_add_f32_e32 v234, v237, v234
	v_add_f32_e32 v250, v226, v234
	v_cvt_pk_bf16_f32 v230, v76, v77
	v_cvt_pk_bf16_f32 v231, v78, v79
	v_cvt_pk_bf16_f32 v232, v72, v73
	v_cvt_pk_bf16_f32 v233, v74, v75
	v_cvt_pk_bf16_f32 v238, v68, v69
	v_cvt_pk_bf16_f32 v239, v70, v71
	v_cvt_pk_bf16_f32 v240, v64, v65
	v_cvt_pk_bf16_f32 v241, v66, v67
	v_mov_b32_e32 v251, v250
	global_store_dwordx4 v[248:249], v[230:233], off
	global_store_dwordx4 v[248:249], v[238:241], off offset:256
	v_permlane16_swap_b32_e32 v251, v250
	v_lshl_add_u64 v[248:249], v[248:249], 0, s[8:9]
	s_nop 0
	v_add_f32_e32 v250, v250, v251
	v_mov_b32_e32 v251, v250
	s_nop 1
	v_permlane32_swap_b32_e32 v251, v250
	s_nop 1
	v_add_f32_e32 v250, v250, v251
	s_and_saveexec_b64 s[20:21], s[2:3]
	global_store_dword v[242:243], v250, off offset:3072
	s_or_b64 exec, exec, s[20:21]
	s_waitcnt vmcnt(18)
	v_lshlrev_b32_e32 v226, 16, v192
	v_and_b32_e32 v227, 0xffff0000, v192
	v_lshlrev_b32_e32 v228, 16, v193
	v_and_b32_e32 v229, 0xffff0000, v193
	v_lshlrev_b32_e32 v230, 16, v194
	v_and_b32_e32 v231, 0xffff0000, v194
	v_lshlrev_b32_e32 v232, 16, v195
	v_and_b32_e32 v233, 0xffff0000, v195
	v_lshlrev_b32_e32 v234, 16, v196
	v_and_b32_e32 v235, 0xffff0000, v196
	v_lshlrev_b32_e32 v236, 16, v197
	v_and_b32_e32 v237, 0xffff0000, v197
	v_lshlrev_b32_e32 v238, 16, v198
	v_and_b32_e32 v239, 0xffff0000, v198
	v_lshlrev_b32_e32 v240, 16, v199
	v_and_b32_e32 v241, 0xffff0000, v199
	v_pk_add_f32 v[60:61], v[60:61], v[226:227]
	v_pk_add_f32 v[62:63], v[62:63], v[228:229]
	v_pk_add_f32 v[56:57], v[56:57], v[230:231]
	v_pk_add_f32 v[58:59], v[58:59], v[232:233]
	v_pk_add_f32 v[52:53], v[52:53], v[234:235]
	v_pk_add_f32 v[54:55], v[54:55], v[236:237]
	v_pk_add_f32 v[48:49], v[48:49], v[238:239]
	v_pk_add_f32 v[50:51], v[50:51], v[240:241]
	v_mul_f32_e32 v226, v61, v61
	v_mul_f32_e32 v227, v63, v63
	v_mul_f32_e32 v228, v57, v57
	v_mul_f32_e32 v229, v59, v59
	v_mul_f32_e32 v234, v53, v53
	v_mul_f32_e32 v235, v55, v55
	v_mul_f32_e32 v236, v49, v49
	v_mul_f32_e32 v237, v51, v51
	v_fmac_f32_e32 v226, v60, v60
	v_fmac_f32_e32 v227, v62, v62
	v_fmac_f32_e32 v228, v56, v56
	v_fmac_f32_e32 v229, v58, v58
	v_fmac_f32_e32 v234, v52, v52
	v_fmac_f32_e32 v235, v54, v54
	v_fmac_f32_e32 v236, v48, v48
	v_fmac_f32_e32 v237, v50, v50
	v_add_f32_e32 v226, v226, v227
	v_add_f32_e32 v234, v234, v235
	v_add_f32_e32 v226, v228, v226
	v_add_f32_e32 v234, v236, v234
	v_add_f32_e32 v226, v229, v226
	v_add_f32_e32 v234, v237, v234
	v_add_f32_e32 v250, v226, v234
	v_cvt_pk_bf16_f32 v230, v60, v61
	v_cvt_pk_bf16_f32 v231, v62, v63
	v_cvt_pk_bf16_f32 v232, v56, v57
	v_cvt_pk_bf16_f32 v233, v58, v59
	v_cvt_pk_bf16_f32 v238, v52, v53
	v_cvt_pk_bf16_f32 v239, v54, v55
	v_cvt_pk_bf16_f32 v240, v48, v49
	v_cvt_pk_bf16_f32 v241, v50, v51
	v_mov_b32_e32 v251, v250
	global_store_dwordx4 v[248:249], v[230:233], off
	global_store_dwordx4 v[248:249], v[238:241], off offset:256
	v_permlane16_swap_b32_e32 v251, v250
	v_lshl_add_u64 v[248:249], v[248:249], 0, s[28:29]
	s_nop 0
	v_add_f32_e32 v250, v250, v251
	v_mov_b32_e32 v251, v250
	s_nop 1
	v_permlane32_swap_b32_e32 v251, v250
	s_nop 1
	v_add_f32_e32 v250, v250, v251
	s_and_saveexec_b64 s[20:21], s[2:3]
	global_store_dword v[244:245], v250, off
	s_or_b64 exec, exec, s[20:21]
	s_waitcnt vmcnt(19)
	v_lshlrev_b32_e32 v226, 16, v200
	v_and_b32_e32 v227, 0xffff0000, v200
	v_lshlrev_b32_e32 v228, 16, v201
	v_and_b32_e32 v229, 0xffff0000, v201
	v_lshlrev_b32_e32 v230, 16, v202
	v_and_b32_e32 v231, 0xffff0000, v202
	v_lshlrev_b32_e32 v232, 16, v203
	v_and_b32_e32 v233, 0xffff0000, v203
	v_lshlrev_b32_e32 v234, 16, v204
	v_and_b32_e32 v235, 0xffff0000, v204
	v_lshlrev_b32_e32 v236, 16, v205
	v_and_b32_e32 v237, 0xffff0000, v205
	v_lshlrev_b32_e32 v238, 16, v206
	v_and_b32_e32 v239, 0xffff0000, v206
	v_lshlrev_b32_e32 v240, 16, v207
	v_and_b32_e32 v241, 0xffff0000, v207
	v_pk_add_f32 v[44:45], v[44:45], v[226:227]
	v_pk_add_f32 v[46:47], v[46:47], v[228:229]
	v_pk_add_f32 v[40:41], v[40:41], v[230:231]
	v_pk_add_f32 v[42:43], v[42:43], v[232:233]
	v_pk_add_f32 v[36:37], v[36:37], v[234:235]
	v_pk_add_f32 v[38:39], v[38:39], v[236:237]
	v_pk_add_f32 v[32:33], v[32:33], v[238:239]
	v_pk_add_f32 v[34:35], v[34:35], v[240:241]
	v_mul_f32_e32 v226, v45, v45
	v_mul_f32_e32 v227, v47, v47
	v_mul_f32_e32 v228, v41, v41
	v_mul_f32_e32 v229, v43, v43
	v_mul_f32_e32 v234, v37, v37
	v_mul_f32_e32 v235, v39, v39
	v_mul_f32_e32 v236, v33, v33
	v_mul_f32_e32 v237, v35, v35
	v_fmac_f32_e32 v226, v44, v44
	v_fmac_f32_e32 v227, v46, v46
	v_fmac_f32_e32 v228, v40, v40
	v_fmac_f32_e32 v229, v42, v42
	v_fmac_f32_e32 v234, v36, v36
	v_fmac_f32_e32 v235, v38, v38
	v_fmac_f32_e32 v236, v32, v32
	v_fmac_f32_e32 v237, v34, v34
	v_add_f32_e32 v226, v226, v227
	v_add_f32_e32 v234, v234, v235
	v_add_f32_e32 v226, v228, v226
	v_add_f32_e32 v234, v236, v234
	v_add_f32_e32 v226, v229, v226
	v_add_f32_e32 v234, v237, v234
	v_add_f32_e32 v250, v226, v234
	v_cvt_pk_bf16_f32 v230, v44, v45
	v_cvt_pk_bf16_f32 v231, v46, v47
	v_cvt_pk_bf16_f32 v232, v40, v41
	v_cvt_pk_bf16_f32 v233, v42, v43
	v_cvt_pk_bf16_f32 v238, v36, v37
	v_cvt_pk_bf16_f32 v239, v38, v39
	v_cvt_pk_bf16_f32 v240, v32, v33
	v_cvt_pk_bf16_f32 v241, v34, v35
	v_mov_b32_e32 v251, v250
	global_store_dwordx4 v[248:249], v[230:233], off
	global_store_dwordx4 v[248:249], v[238:241], off offset:256
	v_permlane16_swap_b32_e32 v251, v250
	v_lshl_add_u64 v[248:249], v[248:249], 0, s[28:29]
	s_nop 0
	v_add_f32_e32 v250, v250, v251
	v_mov_b32_e32 v251, v250
	s_nop 1
	v_permlane32_swap_b32_e32 v251, v250
	s_nop 1
	v_add_f32_e32 v250, v250, v251
	s_and_saveexec_b64 s[20:21], s[2:3]
	global_store_dword v[244:245], v250, off offset:1024
	s_or_b64 exec, exec, s[20:21]
	s_waitcnt vmcnt(20)
	v_lshlrev_b32_e32 v226, 16, v208
	v_and_b32_e32 v227, 0xffff0000, v208
	v_lshlrev_b32_e32 v228, 16, v209
	v_and_b32_e32 v229, 0xffff0000, v209
	v_lshlrev_b32_e32 v230, 16, v210
	v_and_b32_e32 v231, 0xffff0000, v210
	v_lshlrev_b32_e32 v232, 16, v211
	v_and_b32_e32 v233, 0xffff0000, v211
	v_lshlrev_b32_e32 v234, 16, v212
	v_and_b32_e32 v235, 0xffff0000, v212
	v_lshlrev_b32_e32 v236, 16, v213
	v_and_b32_e32 v237, 0xffff0000, v213
	v_lshlrev_b32_e32 v238, 16, v214
	v_and_b32_e32 v239, 0xffff0000, v214
	v_lshlrev_b32_e32 v240, 16, v215
	v_and_b32_e32 v241, 0xffff0000, v215
	v_pk_add_f32 v[28:29], v[28:29], v[226:227]
	v_pk_add_f32 v[30:31], v[30:31], v[228:229]
	v_pk_add_f32 v[24:25], v[24:25], v[230:231]
	v_pk_add_f32 v[26:27], v[26:27], v[232:233]
	v_pk_add_f32 v[20:21], v[20:21], v[234:235]
	v_pk_add_f32 v[22:23], v[22:23], v[236:237]
	v_pk_add_f32 v[16:17], v[16:17], v[238:239]
	v_pk_add_f32 v[18:19], v[18:19], v[240:241]
	v_mul_f32_e32 v226, v29, v29
	v_mul_f32_e32 v227, v31, v31
	v_mul_f32_e32 v228, v25, v25
	v_mul_f32_e32 v229, v27, v27
	v_mul_f32_e32 v234, v21, v21
	v_mul_f32_e32 v235, v23, v23
	v_mul_f32_e32 v236, v17, v17
	v_mul_f32_e32 v237, v19, v19
	v_fmac_f32_e32 v226, v28, v28
	v_fmac_f32_e32 v227, v30, v30
	v_fmac_f32_e32 v228, v24, v24
	v_fmac_f32_e32 v229, v26, v26
	v_fmac_f32_e32 v234, v20, v20
	v_fmac_f32_e32 v235, v22, v22
	v_fmac_f32_e32 v236, v16, v16
	v_fmac_f32_e32 v237, v18, v18
	v_add_f32_e32 v226, v226, v227
	v_add_f32_e32 v234, v234, v235
	v_add_f32_e32 v226, v228, v226
	v_add_f32_e32 v234, v236, v234
	v_add_f32_e32 v226, v229, v226
	v_add_f32_e32 v234, v237, v234
	v_add_f32_e32 v250, v226, v234
	v_cvt_pk_bf16_f32 v230, v28, v29
	v_cvt_pk_bf16_f32 v231, v30, v31
	v_cvt_pk_bf16_f32 v232, v24, v25
	v_cvt_pk_bf16_f32 v233, v26, v27
	v_cvt_pk_bf16_f32 v238, v20, v21
	v_cvt_pk_bf16_f32 v239, v22, v23
	v_cvt_pk_bf16_f32 v240, v16, v17
	v_cvt_pk_bf16_f32 v241, v18, v19
	v_mov_b32_e32 v251, v250
	global_store_dwordx4 v[248:249], v[230:233], off
	global_store_dwordx4 v[248:249], v[238:241], off offset:256
	v_permlane16_swap_b32_e32 v251, v250
	v_lshl_add_u64 v[248:249], v[248:249], 0, s[28:29]
	s_nop 0
	v_add_f32_e32 v250, v250, v251
	v_mov_b32_e32 v251, v250
	s_nop 1
	v_permlane32_swap_b32_e32 v251, v250
	s_nop 1
	v_add_f32_e32 v250, v250, v251
	s_and_saveexec_b64 s[20:21], s[2:3]
	global_store_dword v[244:245], v250, off offset:2048
	s_or_b64 exec, exec, s[20:21]
	s_waitcnt vmcnt(21)
	v_lshlrev_b32_e32 v226, 16, v216
	v_and_b32_e32 v227, 0xffff0000, v216
	v_lshlrev_b32_e32 v228, 16, v217
	v_and_b32_e32 v229, 0xffff0000, v217
	v_lshlrev_b32_e32 v230, 16, v218
	v_and_b32_e32 v231, 0xffff0000, v218
	v_lshlrev_b32_e32 v232, 16, v219
	v_and_b32_e32 v233, 0xffff0000, v219
	v_lshlrev_b32_e32 v234, 16, v220
	v_and_b32_e32 v235, 0xffff0000, v220
	v_lshlrev_b32_e32 v236, 16, v221
	v_and_b32_e32 v237, 0xffff0000, v221
	v_lshlrev_b32_e32 v238, 16, v222
	v_and_b32_e32 v239, 0xffff0000, v222
	v_lshlrev_b32_e32 v240, 16, v223
	v_and_b32_e32 v241, 0xffff0000, v223
	v_pk_add_f32 v[12:13], v[12:13], v[226:227]
	v_pk_add_f32 v[14:15], v[14:15], v[228:229]
	v_pk_add_f32 v[8:9], v[8:9], v[230:231]
	v_pk_add_f32 v[10:11], v[10:11], v[232:233]
	v_pk_add_f32 v[4:5], v[4:5], v[234:235]
	v_pk_add_f32 v[6:7], v[6:7], v[236:237]
	v_pk_add_f32 v[0:1], v[0:1], v[238:239]
	v_pk_add_f32 v[2:3], v[2:3], v[240:241]
	v_mul_f32_e32 v226, v13, v13
	v_mul_f32_e32 v227, v15, v15
	v_mul_f32_e32 v228, v9, v9
	v_mul_f32_e32 v229, v11, v11
	v_mul_f32_e32 v234, v5, v5
	v_mul_f32_e32 v235, v7, v7
	v_mul_f32_e32 v236, v1, v1
	v_mul_f32_e32 v237, v3, v3
	v_fmac_f32_e32 v226, v12, v12
	v_fmac_f32_e32 v227, v14, v14
	v_fmac_f32_e32 v228, v8, v8
	v_fmac_f32_e32 v229, v10, v10
	v_fmac_f32_e32 v234, v4, v4
	v_fmac_f32_e32 v235, v6, v6
	v_fmac_f32_e32 v236, v0, v0
	v_fmac_f32_e32 v237, v2, v2
	v_add_f32_e32 v226, v226, v227
	v_add_f32_e32 v234, v234, v235
	v_add_f32_e32 v226, v228, v226
	v_add_f32_e32 v234, v236, v234
	v_add_f32_e32 v226, v229, v226
	v_add_f32_e32 v234, v237, v234
	v_add_f32_e32 v250, v226, v234
	v_cvt_pk_bf16_f32 v230, v12, v13
	v_cvt_pk_bf16_f32 v231, v14, v15
	v_cvt_pk_bf16_f32 v232, v8, v9
	v_cvt_pk_bf16_f32 v233, v10, v11
	v_cvt_pk_bf16_f32 v238, v4, v5
	v_cvt_pk_bf16_f32 v239, v6, v7
	v_cvt_pk_bf16_f32 v240, v0, v1
	v_cvt_pk_bf16_f32 v241, v2, v3
	v_mov_b32_e32 v251, v250
	global_store_dwordx4 v[248:249], v[230:233], off
	global_store_dwordx4 v[248:249], v[238:241], off offset:256
	v_permlane16_swap_b32_e32 v251, v250
	s_nop 0
	s_nop 0
	v_add_f32_e32 v250, v250, v251
	v_mov_b32_e32 v251, v250
	s_nop 1
	v_permlane32_swap_b32_e32 v251, v250
	s_nop 1
	v_add_f32_e32 v250, v250, v251
	s_and_saveexec_b64 s[20:21], s[2:3]
	global_store_dword v[244:245], v250, off offset:3072
	s_or_b64 exec, exec, s[20:21]
	s_and_b64 vcc, exec, s[4:5]
	s_mov_b64 s[4:5], -1
	s_cbranch_vccnz .LBB0_900
	s_andn2_b64 vcc, exec, s[10:11]
	s_cbranch_vccnz .LBB0_899
	s_barrier
	s_branch .LBB0_899
